# in-proj GEMM: per-tile row statistics prefetched at the top of the tile iteration into otherwise unused registers (on top of the fused phase-11 version)
# baseline (speedup 1.0000x reference)
.LBB0_171:
	v_lshl_add_u32 v232, s2, 8, v159
	v_ashrrev_i32_e32 v233, 31, v232
	v_lshl_add_u64 v[232:233], v[232:233], 2, s[8:9]
	global_load_dword v234, v[232:233], off
	global_load_dword v235, v[232:233], off offset:64
	global_load_dword v236, v[232:233], off offset:128
	global_load_dword v237, v[232:233], off offset:192
	global_load_dword v238, v[232:233], off offset:512
	global_load_dword v225, v[232:233], off offset:576
	global_load_dword v241, v[232:233], off offset:640
	global_load_dword v248, v[232:233], off offset:704
	s_add_i32 s48, s48, 1
	v_readlane_b32 s3, v249, 24
	v_readlane_b32 s7, v249, 0
	s_mul_i32 s3, s48, s3
	s_mul_hi_u32 s6, s48, s7
	s_add_i32 s6, s6, s3
	s_mul_i32 s3, s48, s7
	v_readlane_b32 s18, v253, 15
	v_readlane_b32 s19, v253, 16
	s_add_u32 s18, s3, s18
	s_addc_u32 s19, s6, s19
	v_mov_b64_e32 v[2:3], s[90:91]
	v_cmp_ge_i64_e32 vcc, s[18:19], v[2:3]
	v_cmp_lt_i64_e64 s[6:7], s[18:19], v[2:3]
	s_cbranch_vccnz .LBB0_173
	s_ashr_i32 s3, s18, 31
	s_lshr_b32 s3, s3, 29
	s_add_i32 s3, s18, s3
	s_ashr_i32 s14, s3, 3
	s_and_b32 s3, s3, -8
	s_sub_i32 s3, s18, s3
	s_lshr_b32 s15, s3, 31
	s_or_b32 s15, s29, s15
	s_mul_i32 s3, s15, s3
	s_add_i32 s3, s3, s14
	s_abs_i32 s15, s3
	s_mul_hi_u32 s16, s15, s30
	s_mul_i32 s17, s16, s29
	s_sub_i32 s15, s15, s17
	s_ashr_i32 s14, s3, 31
	s_add_i32 s17, s16, 1
	s_sub_i32 s18, s15, s29
	s_cmp_ge_u32 s15, s29
	s_cselect_b32 s16, s17, s16
	s_cselect_b32 s15, s18, s15
	s_add_i32 s17, s16, 1
	s_cmp_ge_u32 s15, s29
	s_cselect_b32 s15, s17, s16
	s_xor_b32 s15, s15, s14
	s_sub_i32 s14, s15, s14
	s_lshl_b32 s15, s14, 3
	s_sub_i32 s16, 64, s15
	s_min_i32 s16, s16, 8
	s_abs_i32 s17, s16
	v_cvt_f32_u32_e32 v0, s17
	s_sub_i32 s19, 0, s17
	s_mul_i32 s14, s14, s29
	s_sub_i32 s3, s3, s14
	v_rcp_iflag_f32_e32 v0, v0
	s_abs_i32 s18, s3
	s_xor_b32 s14, s3, s16
	s_ashr_i32 s14, s14, 31
	v_mul_f32_e32 v0, 0x4f7ffffe, v0
	v_cvt_u32_f32_e32 v0, v0
	s_nop 0
	v_readfirstlane_b32 s20, v0
	s_mul_i32 s19, s19, s20
	s_mul_hi_u32 s19, s20, s19
	s_add_i32 s20, s20, s19
	s_mul_hi_u32 s19, s18, s20
	s_mul_i32 s20, s19, s17
	s_sub_i32 s18, s18, s20
	s_add_i32 s20, s19, 1
	s_sub_i32 s21, s18, s17
	s_cmp_ge_u32 s18, s17
	s_cselect_b32 s19, s20, s19
	s_cselect_b32 s18, s21, s18
	s_add_i32 s20, s19, 1
	s_cmp_ge_u32 s18, s17
	s_cselect_b32 s17, s20, s19
	s_xor_b32 s17, s17, s14
	s_sub_i32 s14, s17, s14
	s_mul_i32 s16, s14, s16
	s_sub_i32 s3, s3, s16
	s_add_i32 s16, s3, s15

.LBB0_177:
	v_lshl_add_u32 v174, s2, 8, v159
	v_ashrrev_i32_e32 v175, 31, v174
	v_lshl_add_u64 v[130:131], v[174:175], 2, s[8:9]
	v_mov_b32_e32 v172, v234
	v_mov_b32_e32 v178, v235
	v_mov_b32_e32 v182, v236
	v_mov_b32_e32 v186, v237
	v_mov_b32_e32 v190, v238
	v_mov_b32_e32 v194, v225
	v_mov_b32_e32 v198, v241
	v_mov_b32_e32 v200, v248
	s_mov_b32 s2, 0x800000
	v_or_b32_e32 v170, 16, v174
	v_or_b32_e32 v176, 32, v174
	v_or_b32_e32 v180, 48, v174
	v_add_u32_e32 v184, 0x80, v174
	v_add_u32_e32 v188, 0x90, v174
	v_add_u32_e32 v192, 0xa0, v174
	v_add_u32_e32 v196, 0xb0, v174
	v_ashrrev_i32_e32 v171, 31, v170
	v_ashrrev_i32_e32 v177, 31, v176
	v_ashrrev_i32_e32 v181, 31, v180
	v_ashrrev_i32_e32 v185, 31, v184
	v_ashrrev_i32_e32 v189, 31, v188
	v_ashrrev_i32_e32 v193, 31, v192
	v_ashrrev_i32_e32 v197, 31, v196
	s_cmp_lg_u32 s49, s37
	s_waitcnt vmcnt(0)
	v_fmamk_f32 v172, v172, 0x3a800000, v219
	v_cmp_gt_f32_e32 vcc, s2, v172
	v_mul_f32_e32 v132, 0x4b800000, v172
	s_nop 0
	v_cndmask_b32_e32 v172, v172, v132, vcc
	v_rsq_f32_e32 v172, v172
	s_nop 0
	v_mul_f32_e32 v132, 0x45800000, v172
	v_cndmask_b32_e32 v172, v172, v132, vcc
	v_fmamk_f32 v178, v178, 0x3a800000, v219
	v_cmp_gt_f32_e32 vcc, s2, v178
	v_mul_f32_e32 v132, 0x4b800000, v178
	s_nop 0
	v_cndmask_b32_e32 v178, v178, v132, vcc
	v_rsq_f32_e32 v178, v178
	s_nop 0
	v_mul_f32_e32 v132, 0x45800000, v178
	v_cndmask_b32_e32 v178, v178, v132, vcc
	v_fmamk_f32 v182, v182, 0x3a800000, v219
	v_cmp_gt_f32_e32 vcc, s2, v182
	v_mul_f32_e32 v132, 0x4b800000, v182
	s_nop 0
	v_cndmask_b32_e32 v182, v182, v132, vcc
	v_rsq_f32_e32 v182, v182
	s_nop 0
	v_mul_f32_e32 v132, 0x45800000, v182
	v_cndmask_b32_e32 v182, v182, v132, vcc
	v_fmamk_f32 v186, v186, 0x3a800000, v219
	v_cmp_gt_f32_e32 vcc, s2, v186
	v_mul_f32_e32 v132, 0x4b800000, v186
	s_nop 0
	v_cndmask_b32_e32 v186, v186, v132, vcc
	v_rsq_f32_e32 v186, v186
	s_nop 0
	v_mul_f32_e32 v132, 0x45800000, v186
	v_cndmask_b32_e32 v186, v186, v132, vcc
	v_fmamk_f32 v190, v190, 0x3a800000, v219
	v_cmp_gt_f32_e32 vcc, s2, v190
	v_mul_f32_e32 v132, 0x4b800000, v190
	s_nop 0
	v_cndmask_b32_e32 v190, v190, v132, vcc
	v_rsq_f32_e32 v190, v190
	s_nop 0
	v_mul_f32_e32 v132, 0x45800000, v190
	v_cndmask_b32_e32 v190, v190, v132, vcc
	v_fmamk_f32 v194, v194, 0x3a800000, v219
	v_cmp_gt_f32_e32 vcc, s2, v194
	v_mul_f32_e32 v132, 0x4b800000, v194
	s_nop 0
	v_cndmask_b32_e32 v194, v194, v132, vcc
	v_rsq_f32_e32 v194, v194
	s_nop 0
	v_mul_f32_e32 v132, 0x45800000, v194
	v_cndmask_b32_e32 v194, v194, v132, vcc
	v_fmamk_f32 v198, v198, 0x3a800000, v219
	v_cmp_gt_f32_e32 vcc, s2, v198
	v_mul_f32_e32 v132, 0x4b800000, v198
	s_nop 0
	v_cndmask_b32_e32 v198, v198, v132, vcc
	v_rsq_f32_e32 v198, v198
	s_nop 0
	v_mul_f32_e32 v132, 0x45800000, v198
	v_cndmask_b32_e32 v198, v198, v132, vcc
	v_fmamk_f32 v200, v200, 0x3a800000, v219
	v_cmp_gt_f32_e32 vcc, s2, v200
	v_mul_f32_e32 v132, 0x4b800000, v200
	s_nop 0
	v_cndmask_b32_e32 v200, v200, v132, vcc
	v_rsq_f32_e32 v200, v200
	s_nop 0
	v_mul_f32_e32 v132, 0x45800000, v200
	v_cndmask_b32_e32 v200, v200, v132, vcc
	s_mov_b64 s[2:3], -1
	s_cbranch_scc0 .LBB0_182
	s_lshl_b32 s2, s49, 8
	s_and_b32 s4, s2, 0x300
	s_ashr_i32 s2, s49, 2
	s_ashr_i32 s3, s2, 31
	s_lshl_b64 s[22:23], s[2:3], 25
	v_readlane_b32 s24, v254, 34
	v_readlane_b32 s25, v254, 35
	s_add_u32 s5, s24, s22
	s_addc_u32 s15, s25, s23
	s_cmp_eq_u32 s2, s39
	s_cselect_b32 s17, s44, 0
	s_cselect_b32 s3, s45, 0
	s_cmp_eq_u32 s2, s38
	s_cselect_b32 s3, s43, s3
	s_cselect_b32 s2, s42, s17
	s_cmp_eq_u64 s[2:3], 0
	v_lshlrev_b64 v[212:213], 11, v[174:175]
	v_lshlrev_b64 v[210:211], 11, v[170:171]
	v_lshlrev_b64 v[208:209], 11, v[176:177]
	v_lshlrev_b64 v[206:207], 11, v[180:181]
	v_lshlrev_b32_e32 v0, 1, v158
	v_lshlrev_b64 v[204:205], 11, v[184:185]
	v_lshlrev_b64 v[202:203], 11, v[188:189]
	s_cbranch_scc1 .LBB0_188
	s_lshl_b32 s17, s4, 2
	s_add_u32 s2, s2, s17
	s_addc_u32 s3, s3, 0
	v_lshlrev_b32_e32 v134, 2, v158
	global_load_dwordx4 v[138:141], v134, s[2:3] offset:16
	global_load_dwordx4 v[142:145], v134, s[2:3]
	global_load_dwordx4 v[130:133], v134, s[2:3] offset:528
	s_nop 0
	global_load_dwordx4 v[134:137], v134, s[2:3] offset:512
	s_lshl_b32 s2, s4, 1
	s_add_u32 s2, s5, s2
	s_addc_u32 s3, s15, 0
	v_lshl_add_u64 v[148:149], s[2:3], 0, v[212:213]
	s_waitcnt vmcnt(3)
	v_pk_fma_f32 v[226:227], v[76:77], v[172:173], v[140:141] op_sel_hi:[1,0,1]
	s_waitcnt vmcnt(2)
	v_pk_fma_f32 v[146:147], v[78:79], v[172:173], v[142:143] op_sel_hi:[1,0,1]
	v_pk_fma_f32 v[214:215], v[80:81], v[172:173], v[144:145] op_sel_hi:[1,0,1]
	v_mul_f32_e32 v146, 0xbfb8aa3b, v146
	v_mul_f32_e32 v147, 0xbfb8aa3b, v147
	v_exp_f32_e32 v146, v146
	v_exp_f32_e32 v147, v147
	v_mul_f32_e32 v183, 0xbfb8aa3b, v215
	v_exp_f32_e32 v183, v183
	v_add_f32_e32 v146, 1.0, v146
	v_add_f32_e32 v147, 1.0, v147
	v_rcp_f32_e32 v146, v146
	v_rcp_f32_e32 v147, v147
	v_add_f32_e32 v183, 1.0, v183
	v_rcp_f32_e32 v183, v183
	v_cvt_pk_bf16_f32 v146, v146, v147
	v_mul_f32_e32 v147, 0xbfb8aa3b, v214
	v_lshl_add_u64 v[214:215], v[148:149], 0, v[0:1]
	v_pk_fma_f32 v[148:149], v[74:75], v[172:173], v[138:139] op_sel_hi:[1,0,1]
	v_exp_f32_e32 v147, v147
	v_mul_f32_e32 v148, 0xbfb8aa3b, v148
	v_mul_f32_e32 v149, 0xbfb8aa3b, v149
	v_exp_f32_e32 v148, v148
	v_exp_f32_e32 v149, v149
	v_add_f32_e32 v147, 1.0, v147
	v_rcp_f32_e32 v147, v147
	v_add_f32_e32 v148, 1.0, v148
	v_add_f32_e32 v149, 1.0, v149
	v_rcp_f32_e32 v148, v148
	v_rcp_f32_e32 v149, v149
	v_cvt_pk_bf16_f32 v147, v147, v183
	v_mul_f32_e32 v183, 0xbfb8aa3b, v227
	v_exp_f32_e32 v183, v183
	v_cvt_pk_bf16_f32 v148, v148, v149
	v_mul_f32_e32 v149, 0xbfb8aa3b, v226
	v_exp_f32_e32 v149, v149
	v_add_f32_e32 v183, 1.0, v183
	v_rcp_f32_e32 v183, v183
	s_waitcnt vmcnt(1)
	v_pk_fma_f32 v[226:227], v[124:125], v[172:173], v[132:133] op_sel_hi:[1,0,1]
	v_add_f32_e32 v149, 1.0, v149
	v_rcp_f32_e32 v149, v149
	s_nop 0
	v_cvt_pk_bf16_f32 v149, v149, v183
	global_store_dwordx4 v[214:215], v[146:149], off
	v_mul_f32_e32 v183, 0xbfb8aa3b, v227
	v_exp_f32_e32 v183, v183
	s_waitcnt vmcnt(1)
	v_pk_fma_f32 v[146:147], v[126:127], v[172:173], v[134:135] op_sel_hi:[1,0,1]
	v_pk_fma_f32 v[148:149], v[128:129], v[172:173], v[136:137] op_sel_hi:[1,0,1]
	v_mul_f32_e32 v146, 0xbfb8aa3b, v146
	v_mul_f32_e32 v147, 0xbfb8aa3b, v147
	v_exp_f32_e32 v146, v146
	v_exp_f32_e32 v147, v147
	v_add_f32_e32 v183, 1.0, v183
	v_rcp_f32_e32 v183, v183
	v_add_f32_e32 v146, 1.0, v146
	v_add_f32_e32 v147, 1.0, v147
	v_rcp_f32_e32 v146, v146
	v_rcp_f32_e32 v147, v147
	s_nop 0
	v_cvt_pk_bf16_f32 v146, v146, v147
	v_mul_f32_e32 v147, 0xbfb8aa3b, v148
	v_mul_f32_e32 v148, 0xbfb8aa3b, v149
	v_exp_f32_e32 v147, v147
	v_exp_f32_e32 v148, v148
	v_add_f32_e32 v147, 1.0, v147
	v_add_f32_e32 v148, 1.0, v148
	v_rcp_f32_e32 v147, v147
	v_rcp_f32_e32 v148, v148
	s_nop 0
	v_cvt_pk_bf16_f32 v147, v147, v148
	v_pk_fma_f32 v[148:149], v[122:123], v[172:173], v[130:131] op_sel_hi:[1,0,1]
	s_nop 0
	v_mul_f32_e32 v148, 0xbfb8aa3b, v148
	v_mul_f32_e32 v149, 0xbfb8aa3b, v149
	v_exp_f32_e32 v148, v148
	v_exp_f32_e32 v149, v149
	v_add_f32_e32 v148, 1.0, v148
	v_add_f32_e32 v149, 1.0, v149
	v_rcp_f32_e32 v148, v148
	v_rcp_f32_e32 v149, v149
	s_nop 0
	v_cvt_pk_bf16_f32 v148, v148, v149
	v_mul_f32_e32 v149, 0xbfb8aa3b, v226
	v_exp_f32_e32 v149, v149
	s_nop 0
	v_add_f32_e32 v149, 1.0, v149
	v_rcp_f32_e32 v149, v149
	s_nop 0
	v_cvt_pk_bf16_f32 v149, v149, v183
	global_store_dwordx4 v[214:215], v[146:149], off offset:256
	v_pk_fma_f32 v[214:215], v[70:71], v[178:179], v[142:143] op_sel_hi:[1,0,1]
	s_nop 0
	v_pk_fma_f32 v[148:149], v[72:73], v[178:179], v[144:145] op_sel_hi:[1,0,1]
	v_mul_f32_e32 v183, 0xbfb8aa3b, v214
	v_mul_f32_e32 v148, 0xbfb8aa3b, v148
	v_mul_f32_e32 v149, 0xbfb8aa3b, v149
	v_exp_f32_e32 v148, v148
	v_exp_f32_e32 v149, v149
	v_mul_f32_e32 v187, 0xbfb8aa3b, v215
	v_exp_f32_e32 v183, v183
	v_exp_f32_e32 v187, v187
	v_add_f32_e32 v148, 1.0, v148
	v_add_f32_e32 v149, 1.0, v149
	v_rcp_f32_e32 v148, v148
	v_rcp_f32_e32 v149, v149
	v_add_f32_e32 v183, 1.0, v183
	v_add_f32_e32 v187, 1.0, v187
	v_rcp_f32_e32 v183, v183
	v_rcp_f32_e32 v187, v187
	v_cvt_pk_bf16_f32 v243, v148, v149
	v_pk_fma_f32 v[148:149], v[64:65], v[178:179], v[140:141] op_sel_hi:[1,0,1]
	v_pk_fma_f32 v[214:215], v[62:63], v[178:179], v[138:139] op_sel_hi:[1,0,1]
	v_mul_f32_e32 v148, 0xbfb8aa3b, v148
	v_mul_f32_e32 v149, 0xbfb8aa3b, v149
	v_exp_f32_e32 v148, v148
	v_exp_f32_e32 v149, v149
	v_cvt_pk_bf16_f32 v242, v183, v187
	v_mul_f32_e32 v183, 0xbfb8aa3b, v214
	v_mul_f32_e32 v187, 0xbfb8aa3b, v215
	v_exp_f32_e32 v183, v183
	v_exp_f32_e32 v187, v187
	v_add_f32_e32 v148, 1.0, v148
	v_add_f32_e32 v149, 1.0, v149
	v_rcp_f32_e32 v148, v148
	v_rcp_f32_e32 v149, v149
	v_add_f32_e32 v183, 1.0, v183
	v_add_f32_e32 v187, 1.0, v187
	v_rcp_f32_e32 v183, v183
	v_rcp_f32_e32 v187, v187
	v_cvt_pk_bf16_f32 v245, v148, v149
	v_pk_fma_f32 v[148:149], v[120:121], v[178:179], v[136:137] op_sel_hi:[1,0,1]
	v_pk_fma_f32 v[214:215], v[118:119], v[178:179], v[134:135] op_sel_hi:[1,0,1]
	v_mul_f32_e32 v148, 0xbfb8aa3b, v148
	v_mul_f32_e32 v149, 0xbfb8aa3b, v149
	v_cvt_pk_bf16_f32 v244, v183, v187
	v_mul_f32_e32 v183, 0xbfb8aa3b, v214
	v_mul_f32_e32 v187, 0xbfb8aa3b, v215
	v_exp_f32_e32 v148, v148
	v_exp_f32_e32 v149, v149
	v_exp_f32_e32 v183, v183
	v_exp_f32_e32 v187, v187
	v_add_f32_e32 v148, 1.0, v148
	v_add_f32_e32 v149, 1.0, v149
	v_add_f32_e32 v183, 1.0, v183
	v_add_f32_e32 v187, 1.0, v187
	v_rcp_f32_e32 v148, v148
	v_rcp_f32_e32 v149, v149
	v_rcp_f32_e32 v183, v183
	v_rcp_f32_e32 v187, v187
	v_lshl_add_u64 v[146:147], s[2:3], 0, v[210:211]
	v_lshl_add_u64 v[146:147], v[146:147], 0, v[0:1]
	global_store_dwordx4 v[146:147], v[242:245], off
	v_pk_fma_f32 v[214:215], v[114:115], v[178:179], v[130:131] op_sel_hi:[1,0,1]
	s_nop 0
	v_cvt_pk_bf16_f32 v243, v148, v149
	v_pk_fma_f32 v[148:149], v[116:117], v[178:179], v[132:133] op_sel_hi:[1,0,1]
	v_cvt_pk_bf16_f32 v242, v183, v187
	v_mul_f32_e32 v183, 0xbfb8aa3b, v214
	v_mul_f32_e32 v148, 0xbfb8aa3b, v148
	v_mul_f32_e32 v149, 0xbfb8aa3b, v149
	v_exp_f32_e32 v183, v183
	v_mul_f32_e32 v187, 0xbfb8aa3b, v215
	v_exp_f32_e32 v148, v148
	v_exp_f32_e32 v149, v149
	v_exp_f32_e32 v187, v187
	v_add_f32_e32 v183, 1.0, v183
	v_add_f32_e32 v148, 1.0, v148
	v_add_f32_e32 v149, 1.0, v149
	v_rcp_f32_e32 v183, v183
	v_add_f32_e32 v187, 1.0, v187
	v_rcp_f32_e32 v148, v148
	v_rcp_f32_e32 v149, v149
	v_rcp_f32_e32 v187, v187
	v_pk_fma_f32 v[214:215], v[54:55], v[182:183], v[142:143] op_sel_hi:[1,0,1]
	v_cvt_pk_bf16_f32 v245, v148, v149
	v_pk_fma_f32 v[148:149], v[56:57], v[182:183], v[144:145] op_sel_hi:[1,0,1]
	v_cvt_pk_bf16_f32 v244, v183, v187
	v_mul_f32_e32 v183, 0xbfb8aa3b, v214
	v_mul_f32_e32 v148, 0xbfb8aa3b, v148
	v_mul_f32_e32 v149, 0xbfb8aa3b, v149
	v_exp_f32_e32 v183, v183
	v_mul_f32_e32 v187, 0xbfb8aa3b, v215
	v_exp_f32_e32 v148, v148
	v_exp_f32_e32 v149, v149
	v_exp_f32_e32 v187, v187
	v_add_f32_e32 v183, 1.0, v183
	v_add_f32_e32 v148, 1.0, v148
	v_add_f32_e32 v149, 1.0, v149
	v_rcp_f32_e32 v183, v183
	v_add_f32_e32 v187, 1.0, v187
	v_rcp_f32_e32 v148, v148
	v_rcp_f32_e32 v149, v149
	v_rcp_f32_e32 v187, v187
	global_store_dwordx4 v[146:147], v[242:245], off offset:256
	v_pk_fma_f32 v[214:215], v[50:51], v[182:183], v[138:139] op_sel_hi:[1,0,1]
	v_lshl_add_u64 v[146:147], s[2:3], 0, v[208:209]
	v_cvt_pk_bf16_f32 v243, v148, v149
	v_pk_fma_f32 v[148:149], v[52:53], v[182:183], v[140:141] op_sel_hi:[1,0,1]
	v_cvt_pk_bf16_f32 v242, v183, v187
	v_mul_f32_e32 v183, 0xbfb8aa3b, v214
	v_mul_f32_e32 v148, 0xbfb8aa3b, v148
	v_mul_f32_e32 v149, 0xbfb8aa3b, v149
	v_exp_f32_e32 v183, v183
	v_mul_f32_e32 v187, 0xbfb8aa3b, v215
	v_exp_f32_e32 v148, v148
	v_exp_f32_e32 v149, v149
	v_exp_f32_e32 v187, v187
	v_add_f32_e32 v183, 1.0, v183
	v_add_f32_e32 v148, 1.0, v148
	v_add_f32_e32 v149, 1.0, v149
	v_rcp_f32_e32 v183, v183
	v_add_f32_e32 v187, 1.0, v187
	v_rcp_f32_e32 v148, v148
	v_rcp_f32_e32 v149, v149
	v_rcp_f32_e32 v187, v187
	v_pk_fma_f32 v[214:215], v[110:111], v[182:183], v[134:135] op_sel_hi:[1,0,1]
	v_lshl_add_u64 v[146:147], v[146:147], 0, v[0:1]
	v_cvt_pk_bf16_f32 v245, v148, v149
	v_pk_fma_f32 v[148:149], v[112:113], v[182:183], v[136:137] op_sel_hi:[1,0,1]
	v_cvt_pk_bf16_f32 v244, v183, v187
	v_mul_f32_e32 v183, 0xbfb8aa3b, v214
	v_mul_f32_e32 v148, 0xbfb8aa3b, v148
	v_mul_f32_e32 v149, 0xbfb8aa3b, v149
	v_exp_f32_e32 v183, v183
	v_mul_f32_e32 v187, 0xbfb8aa3b, v215
	v_exp_f32_e32 v148, v148
	v_exp_f32_e32 v149, v149
	v_exp_f32_e32 v187, v187
	v_add_f32_e32 v183, 1.0, v183
	v_add_f32_e32 v148, 1.0, v148
	v_add_f32_e32 v149, 1.0, v149
	v_rcp_f32_e32 v183, v183
	v_add_f32_e32 v187, 1.0, v187
	v_rcp_f32_e32 v148, v148
	v_rcp_f32_e32 v149, v149
	v_rcp_f32_e32 v187, v187
	global_store_dwordx4 v[146:147], v[242:245], off
	v_pk_fma_f32 v[214:215], v[106:107], v[182:183], v[130:131] op_sel_hi:[1,0,1]
	s_nop 0
	v_cvt_pk_bf16_f32 v243, v148, v149
	v_pk_fma_f32 v[148:149], v[108:109], v[182:183], v[132:133] op_sel_hi:[1,0,1]
	v_cvt_pk_bf16_f32 v242, v183, v187
	v_mul_f32_e32 v187, 0xbfb8aa3b, v215
	v_mul_f32_e32 v148, 0xbfb8aa3b, v148
	v_mul_f32_e32 v149, 0xbfb8aa3b, v149
	v_mul_f32_e32 v183, 0xbfb8aa3b, v214
	v_exp_f32_e32 v187, v187
	v_exp_f32_e32 v148, v148
	v_exp_f32_e32 v149, v149
	v_exp_f32_e32 v183, v183
	v_add_f32_e32 v187, 1.0, v187
	v_add_f32_e32 v148, 1.0, v148
	v_add_f32_e32 v149, 1.0, v149
	v_add_f32_e32 v183, 1.0, v183
	v_rcp_f32_e32 v187, v187
	v_rcp_f32_e32 v148, v148
	v_rcp_f32_e32 v149, v149
	v_rcp_f32_e32 v183, v183
	v_pk_fma_f32 v[214:215], v[42:43], v[186:187], v[142:143] op_sel_hi:[1,0,1]
	v_cvt_pk_bf16_f32 v245, v148, v149
	v_pk_fma_f32 v[148:149], v[44:45], v[186:187], v[144:145] op_sel_hi:[1,0,1]
	v_cvt_pk_bf16_f32 v244, v183, v187
	v_mul_f32_e32 v187, 0xbfb8aa3b, v215
	v_mul_f32_e32 v148, 0xbfb8aa3b, v148
	v_mul_f32_e32 v149, 0xbfb8aa3b, v149
	v_mul_f32_e32 v183, 0xbfb8aa3b, v214
	v_exp_f32_e32 v187, v187
	v_exp_f32_e32 v148, v148
	v_exp_f32_e32 v149, v149
	v_exp_f32_e32 v183, v183
	v_add_f32_e32 v187, 1.0, v187
	v_add_f32_e32 v148, 1.0, v148
	v_add_f32_e32 v149, 1.0, v149
	v_add_f32_e32 v183, 1.0, v183
	v_rcp_f32_e32 v187, v187
	v_rcp_f32_e32 v148, v148
	v_rcp_f32_e32 v149, v149
	v_rcp_f32_e32 v183, v183
	global_store_dwordx4 v[146:147], v[242:245], off offset:256
	v_pk_fma_f32 v[214:215], v[34:35], v[186:187], v[138:139] op_sel_hi:[1,0,1]
	v_lshl_add_u64 v[146:147], s[2:3], 0, v[206:207]
	v_cvt_pk_bf16_f32 v243, v148, v149
	v_pk_fma_f32 v[148:149], v[36:37], v[186:187], v[140:141] op_sel_hi:[1,0,1]
	v_cvt_pk_bf16_f32 v242, v183, v187
	v_mul_f32_e32 v187, 0xbfb8aa3b, v215
	v_mul_f32_e32 v148, 0xbfb8aa3b, v148
	v_mul_f32_e32 v149, 0xbfb8aa3b, v149
	v_mul_f32_e32 v183, 0xbfb8aa3b, v214
	v_exp_f32_e32 v187, v187
	v_exp_f32_e32 v148, v148
	v_exp_f32_e32 v149, v149
	v_exp_f32_e32 v183, v183
	v_add_f32_e32 v187, 1.0, v187
	v_add_f32_e32 v148, 1.0, v148
	v_add_f32_e32 v149, 1.0, v149
	v_add_f32_e32 v183, 1.0, v183
	v_rcp_f32_e32 v187, v187
	v_rcp_f32_e32 v148, v148
	v_rcp_f32_e32 v149, v149
	v_rcp_f32_e32 v183, v183
	v_pk_fma_f32 v[214:215], v[102:103], v[186:187], v[134:135] op_sel_hi:[1,0,1]
	v_lshl_add_u64 v[146:147], v[146:147], 0, v[0:1]
	v_cvt_pk_bf16_f32 v245, v148, v149
	v_pk_fma_f32 v[148:149], v[104:105], v[186:187], v[136:137] op_sel_hi:[1,0,1]
	v_cvt_pk_bf16_f32 v244, v183, v187
	v_mul_f32_e32 v187, 0xbfb8aa3b, v215
	v_mul_f32_e32 v148, 0xbfb8aa3b, v148
	v_mul_f32_e32 v149, 0xbfb8aa3b, v149
	v_exp_f32_e32 v187, v187
	v_exp_f32_e32 v148, v148
	v_exp_f32_e32 v149, v149
	global_store_dwordx4 v[146:147], v[242:245], off
	v_add_f32_e32 v187, 1.0, v187
	v_add_f32_e32 v148, 1.0, v148
	v_add_f32_e32 v149, 1.0, v149
	v_rcp_f32_e32 v187, v187
	v_rcp_f32_e32 v148, v148
	v_rcp_f32_e32 v149, v149
	v_mul_f32_e32 v183, 0xbfb8aa3b, v214
	v_exp_f32_e32 v183, v183
	v_pk_fma_f32 v[214:215], v[98:99], v[186:187], v[130:131] op_sel_hi:[1,0,1]
	v_cvt_pk_bf16_f32 v243, v148, v149
	v_pk_fma_f32 v[148:149], v[100:101], v[186:187], v[132:133] op_sel_hi:[1,0,1]
	v_add_f32_e32 v183, 1.0, v183
	v_mul_f32_e32 v148, 0xbfb8aa3b, v148
	v_mul_f32_e32 v149, 0xbfb8aa3b, v149
	v_exp_f32_e32 v148, v148
	v_exp_f32_e32 v149, v149
	v_rcp_f32_e32 v183, v183
	v_add_f32_e32 v148, 1.0, v148
	v_add_f32_e32 v149, 1.0, v149
	v_rcp_f32_e32 v148, v148
	v_rcp_f32_e32 v149, v149
	v_cvt_pk_bf16_f32 v242, v183, v187
	v_mul_f32_e32 v183, 0xbfb8aa3b, v214
	v_mul_f32_e32 v187, 0xbfb8aa3b, v215
	v_cvt_pk_bf16_f32 v245, v148, v149
	v_pk_fma_f32 v[148:149], v[32:33], v[190:191], v[144:145] op_sel_hi:[1,0,1]
	v_exp_f32_e32 v183, v183
	v_exp_f32_e32 v187, v187
	v_mul_f32_e32 v148, 0xbfb8aa3b, v148
	v_mul_f32_e32 v149, 0xbfb8aa3b, v149
	v_exp_f32_e32 v148, v148
	v_exp_f32_e32 v149, v149
	v_add_f32_e32 v183, 1.0, v183
	v_add_f32_e32 v187, 1.0, v187
	v_rcp_f32_e32 v183, v183
	v_rcp_f32_e32 v187, v187
	v_add_f32_e32 v148, 1.0, v148
	v_add_f32_e32 v149, 1.0, v149
	v_rcp_f32_e32 v148, v148
	v_rcp_f32_e32 v149, v149
	v_cvt_pk_bf16_f32 v244, v183, v187
	global_store_dwordx4 v[146:147], v[242:245], off offset:256
	v_pk_fma_f32 v[214:215], v[30:31], v[190:191], v[142:143] op_sel_hi:[1,0,1]
	v_lshl_add_u64 v[146:147], s[2:3], 0, v[204:205]
	v_cvt_pk_bf16_f32 v243, v148, v149
	v_pk_fma_f32 v[148:149], v[28:29], v[190:191], v[140:141] op_sel_hi:[1,0,1]
	v_mul_f32_e32 v183, 0xbfb8aa3b, v214
	v_mul_f32_e32 v187, 0xbfb8aa3b, v215
	v_mul_f32_e32 v148, 0xbfb8aa3b, v148
	v_mul_f32_e32 v149, 0xbfb8aa3b, v149
	v_exp_f32_e32 v183, v183
	v_exp_f32_e32 v187, v187
	v_exp_f32_e32 v148, v148
	v_exp_f32_e32 v149, v149
	v_add_f32_e32 v183, 1.0, v183
	v_add_f32_e32 v187, 1.0, v187
	v_add_f32_e32 v148, 1.0, v148
	v_add_f32_e32 v149, 1.0, v149
	v_rcp_f32_e32 v183, v183
	v_rcp_f32_e32 v187, v187
	v_rcp_f32_e32 v148, v148
	v_rcp_f32_e32 v149, v149
	v_pk_fma_f32 v[214:215], v[26:27], v[190:191], v[138:139] op_sel_hi:[1,0,1]
	v_cvt_pk_bf16_f32 v242, v183, v187
	v_mul_f32_e32 v183, 0xbfb8aa3b, v214
	v_mul_f32_e32 v187, 0xbfb8aa3b, v215
	v_cvt_pk_bf16_f32 v245, v148, v149
	v_pk_fma_f32 v[148:149], v[96:97], v[190:191], v[136:137] op_sel_hi:[1,0,1]
	v_exp_f32_e32 v183, v183
	v_exp_f32_e32 v187, v187
	v_mul_f32_e32 v148, 0xbfb8aa3b, v148
	v_mul_f32_e32 v149, 0xbfb8aa3b, v149
	v_exp_f32_e32 v148, v148
	v_exp_f32_e32 v149, v149
	v_add_f32_e32 v183, 1.0, v183
	v_add_f32_e32 v187, 1.0, v187
	v_rcp_f32_e32 v183, v183
	v_rcp_f32_e32 v187, v187
	v_add_f32_e32 v148, 1.0, v148
	v_add_f32_e32 v149, 1.0, v149
	v_rcp_f32_e32 v148, v148
	v_rcp_f32_e32 v149, v149
	v_lshl_add_u64 v[146:147], v[146:147], 0, v[0:1]
	v_cvt_pk_bf16_f32 v244, v183, v187
	global_store_dwordx4 v[146:147], v[242:245], off
	v_pk_fma_f32 v[214:215], v[94:95], v[190:191], v[134:135] op_sel_hi:[1,0,1]
	s_nop 0
	v_cvt_pk_bf16_f32 v243, v148, v149
	v_pk_fma_f32 v[148:149], v[92:93], v[190:191], v[132:133] op_sel_hi:[1,0,1]
	v_mul_f32_e32 v183, 0xbfb8aa3b, v214
	v_mul_f32_e32 v187, 0xbfb8aa3b, v215
	v_mul_f32_e32 v148, 0xbfb8aa3b, v148
	v_mul_f32_e32 v149, 0xbfb8aa3b, v149
	v_exp_f32_e32 v183, v183
	v_exp_f32_e32 v187, v187
	v_exp_f32_e32 v148, v148
	v_exp_f32_e32 v149, v149
	v_add_f32_e32 v183, 1.0, v183
	v_add_f32_e32 v187, 1.0, v187
	v_add_f32_e32 v148, 1.0, v148
	v_add_f32_e32 v149, 1.0, v149
	v_rcp_f32_e32 v183, v183
	v_rcp_f32_e32 v187, v187
	v_rcp_f32_e32 v148, v148
	v_rcp_f32_e32 v149, v149
	v_pk_fma_f32 v[214:215], v[90:91], v[190:191], v[130:131] op_sel_hi:[1,0,1]
	v_cvt_pk_bf16_f32 v242, v183, v187
	v_mul_f32_e32 v183, 0xbfb8aa3b, v214
	v_mul_f32_e32 v187, 0xbfb8aa3b, v215
	v_cvt_pk_bf16_f32 v245, v148, v149
	v_pk_fma_f32 v[148:149], v[24:25], v[194:195], v[144:145] op_sel_hi:[1,0,1]
	v_exp_f32_e32 v183, v183
	v_exp_f32_e32 v187, v187
	v_mul_f32_e32 v148, 0xbfb8aa3b, v148
	v_mul_f32_e32 v149, 0xbfb8aa3b, v149
	v_exp_f32_e32 v148, v148
	v_exp_f32_e32 v149, v149
	v_add_f32_e32 v183, 1.0, v183
	v_add_f32_e32 v187, 1.0, v187
	v_rcp_f32_e32 v183, v183
	v_rcp_f32_e32 v187, v187
	v_add_f32_e32 v148, 1.0, v148
	v_add_f32_e32 v149, 1.0, v149
	v_rcp_f32_e32 v148, v148
	v_rcp_f32_e32 v149, v149
	v_cvt_pk_bf16_f32 v244, v183, v187
	global_store_dwordx4 v[146:147], v[242:245], off offset:256
	v_pk_fma_f32 v[214:215], v[22:23], v[194:195], v[142:143] op_sel_hi:[1,0,1]
	v_lshl_add_u64 v[146:147], s[2:3], 0, v[202:203]
	v_cvt_pk_bf16_f32 v243, v148, v149
	v_pk_fma_f32 v[148:149], v[20:21], v[194:195], v[140:141] op_sel_hi:[1,0,1]
	v_mul_f32_e32 v183, 0xbfb8aa3b, v214
	v_mul_f32_e32 v187, 0xbfb8aa3b, v215
	v_mul_f32_e32 v148, 0xbfb8aa3b, v148
	v_mul_f32_e32 v149, 0xbfb8aa3b, v149
	v_exp_f32_e32 v183, v183
	v_exp_f32_e32 v187, v187
	v_exp_f32_e32 v148, v148
	v_exp_f32_e32 v149, v149
	v_add_f32_e32 v183, 1.0, v183
	v_add_f32_e32 v187, 1.0, v187
	v_add_f32_e32 v148, 1.0, v148
	v_add_f32_e32 v149, 1.0, v149
	v_rcp_f32_e32 v183, v183
	v_rcp_f32_e32 v187, v187
	v_rcp_f32_e32 v148, v148
	v_rcp_f32_e32 v149, v149
	v_pk_fma_f32 v[214:215], v[18:19], v[194:195], v[138:139] op_sel_hi:[1,0,1]
	v_cvt_pk_bf16_f32 v242, v183, v187
	v_mul_f32_e32 v183, 0xbfb8aa3b, v214
	v_mul_f32_e32 v187, 0xbfb8aa3b, v215
	v_cvt_pk_bf16_f32 v245, v148, v149
	v_pk_fma_f32 v[148:149], v[88:89], v[194:195], v[136:137] op_sel_hi:[1,0,1]
	v_exp_f32_e32 v183, v183
	v_exp_f32_e32 v187, v187
	v_mul_f32_e32 v148, 0xbfb8aa3b, v148
	v_mul_f32_e32 v149, 0xbfb8aa3b, v149
	v_exp_f32_e32 v148, v148
	v_exp_f32_e32 v149, v149
	v_add_f32_e32 v183, 1.0, v183
	v_add_f32_e32 v187, 1.0, v187
	v_rcp_f32_e32 v183, v183
	v_rcp_f32_e32 v187, v187
	v_add_f32_e32 v148, 1.0, v148
	v_add_f32_e32 v149, 1.0, v149
	v_rcp_f32_e32 v148, v148
	v_rcp_f32_e32 v149, v149
	v_lshl_add_u64 v[146:147], v[146:147], 0, v[0:1]
	v_cvt_pk_bf16_f32 v244, v183, v187
	global_store_dwordx4 v[146:147], v[242:245], off
	v_pk_fma_f32 v[214:215], v[86:87], v[194:195], v[134:135] op_sel_hi:[1,0,1]
	s_nop 0
	v_cvt_pk_bf16_f32 v243, v148, v149
	v_pk_fma_f32 v[148:149], v[84:85], v[194:195], v[132:133] op_sel_hi:[1,0,1]
	v_mul_f32_e32 v183, 0xbfb8aa3b, v214
	v_mul_f32_e32 v187, 0xbfb8aa3b, v215
	v_mul_f32_e32 v148, 0xbfb8aa3b, v148
	v_mul_f32_e32 v149, 0xbfb8aa3b, v149
	v_exp_f32_e32 v183, v183
	v_exp_f32_e32 v187, v187
	v_exp_f32_e32 v148, v148
	v_exp_f32_e32 v149, v149
	v_add_f32_e32 v183, 1.0, v183
	v_add_f32_e32 v187, 1.0, v187
	v_add_f32_e32 v148, 1.0, v148
	v_add_f32_e32 v149, 1.0, v149
	v_rcp_f32_e32 v183, v183
	v_rcp_f32_e32 v187, v187
	v_rcp_f32_e32 v148, v148
	v_rcp_f32_e32 v149, v149
	v_pk_fma_f32 v[214:215], v[82:83], v[194:195], v[130:131] op_sel_hi:[1,0,1]
	v_cvt_pk_bf16_f32 v242, v183, v187
	v_mul_f32_e32 v183, 0xbfb8aa3b, v214
	v_mul_f32_e32 v187, 0xbfb8aa3b, v215
	v_cvt_pk_bf16_f32 v245, v148, v149
	v_pk_fma_f32 v[148:149], v[16:17], v[198:199], v[144:145] op_sel_hi:[1,0,1]
	v_exp_f32_e32 v183, v183
	v_exp_f32_e32 v187, v187
	v_mul_f32_e32 v148, 0xbfb8aa3b, v148
	v_mul_f32_e32 v149, 0xbfb8aa3b, v149
	v_exp_f32_e32 v148, v148
	v_exp_f32_e32 v149, v149
	v_add_f32_e32 v183, 1.0, v183
	v_add_f32_e32 v187, 1.0, v187
	v_rcp_f32_e32 v183, v183
	v_rcp_f32_e32 v187, v187
	v_add_f32_e32 v148, 1.0, v148
	v_add_f32_e32 v149, 1.0, v149
	v_rcp_f32_e32 v148, v148
	v_rcp_f32_e32 v149, v149
	v_cvt_pk_bf16_f32 v244, v183, v187
	global_store_dwordx4 v[146:147], v[242:245], off offset:256
	v_pk_fma_f32 v[214:215], v[14:15], v[198:199], v[142:143] op_sel_hi:[1,0,1]
	v_lshlrev_b64 v[146:147], 11, v[192:193]
	v_cvt_pk_bf16_f32 v243, v148, v149
	v_pk_fma_f32 v[148:149], v[12:13], v[198:199], v[140:141] op_sel_hi:[1,0,1]
	v_mul_f32_e32 v183, 0xbfb8aa3b, v214
	v_mul_f32_e32 v187, 0xbfb8aa3b, v215
	v_mul_f32_e32 v148, 0xbfb8aa3b, v148
	v_mul_f32_e32 v149, 0xbfb8aa3b, v149
	v_exp_f32_e32 v183, v183
	v_exp_f32_e32 v187, v187
	v_exp_f32_e32 v148, v148
	v_exp_f32_e32 v149, v149
	v_add_f32_e32 v183, 1.0, v183
	v_add_f32_e32 v187, 1.0, v187
	v_add_f32_e32 v148, 1.0, v148
	v_add_f32_e32 v149, 1.0, v149
	v_rcp_f32_e32 v183, v183
	v_rcp_f32_e32 v187, v187
	v_rcp_f32_e32 v148, v148
	v_rcp_f32_e32 v149, v149
	v_pk_fma_f32 v[214:215], v[10:11], v[198:199], v[138:139] op_sel_hi:[1,0,1]
	v_cvt_pk_bf16_f32 v242, v183, v187
	v_mul_f32_e32 v183, 0xbfb8aa3b, v214
	v_mul_f32_e32 v187, 0xbfb8aa3b, v215
	v_cvt_pk_bf16_f32 v245, v148, v149
	v_pk_fma_f32 v[148:149], v[68:69], v[198:199], v[136:137] op_sel_hi:[1,0,1]
	v_exp_f32_e32 v183, v183
	v_exp_f32_e32 v187, v187
	v_mul_f32_e32 v148, 0xbfb8aa3b, v148
	v_mul_f32_e32 v149, 0xbfb8aa3b, v149
	v_exp_f32_e32 v148, v148
	v_exp_f32_e32 v149, v149
	v_add_f32_e32 v183, 1.0, v183
	v_add_f32_e32 v187, 1.0, v187
	v_rcp_f32_e32 v183, v183
	v_rcp_f32_e32 v187, v187
	v_add_f32_e32 v148, 1.0, v148
	v_add_f32_e32 v149, 1.0, v149
	v_rcp_f32_e32 v148, v148
	v_rcp_f32_e32 v149, v149
	v_lshl_add_u64 v[146:147], s[2:3], 0, v[146:147]
	v_pk_fma_f32 v[214:215], v[66:67], v[198:199], v[134:135] op_sel_hi:[1,0,1]
	v_lshl_add_u64 v[146:147], v[146:147], 0, v[0:1]
	v_cvt_pk_bf16_f32 v244, v183, v187
	v_mul_f32_e32 v183, 0xbfb8aa3b, v214
	v_mul_f32_e32 v187, 0xbfb8aa3b, v215
	global_store_dwordx4 v[146:147], v[242:245], off
	v_exp_f32_e32 v183, v183
	v_exp_f32_e32 v187, v187
	v_cvt_pk_bf16_f32 v243, v148, v149
	v_pk_fma_f32 v[148:149], v[60:61], v[198:199], v[132:133] op_sel_hi:[1,0,1]
	v_pk_fma_f32 v[142:143], v[6:7], v[200:201], v[142:143] op_sel_hi:[1,0,1]
	v_mul_f32_e32 v148, 0xbfb8aa3b, v148
	v_mul_f32_e32 v149, 0xbfb8aa3b, v149
	v_pk_fma_f32 v[134:135], v[46:47], v[200:201], v[134:135] op_sel_hi:[1,0,1]
	v_exp_f32_e32 v148, v148
	v_exp_f32_e32 v149, v149
	v_mul_f32_e32 v142, 0xbfb8aa3b, v142
	v_mul_f32_e32 v143, 0xbfb8aa3b, v143
	v_mul_f32_e32 v134, 0xbfb8aa3b, v134
	v_mul_f32_e32 v135, 0xbfb8aa3b, v135
	v_exp_f32_e32 v142, v142
	v_exp_f32_e32 v143, v143
	v_exp_f32_e32 v134, v134
	v_exp_f32_e32 v135, v135
	v_add_f32_e32 v183, 1.0, v183
	v_add_f32_e32 v187, 1.0, v187
	v_rcp_f32_e32 v183, v183
	v_rcp_f32_e32 v187, v187
	v_add_f32_e32 v148, 1.0, v148
	v_add_f32_e32 v149, 1.0, v149
	v_rcp_f32_e32 v148, v148
	v_rcp_f32_e32 v149, v149
	v_add_f32_e32 v142, 1.0, v142
	v_add_f32_e32 v143, 1.0, v143
	v_add_f32_e32 v134, 1.0, v134
	v_add_f32_e32 v135, 1.0, v135
	v_pk_fma_f32 v[214:215], v[58:59], v[198:199], v[130:131] op_sel_hi:[1,0,1]
	v_rcp_f32_e32 v142, v142
	v_rcp_f32_e32 v143, v143
	v_rcp_f32_e32 v134, v134
	v_rcp_f32_e32 v135, v135
	v_cvt_pk_bf16_f32 v242, v183, v187
	v_mul_f32_e32 v183, 0xbfb8aa3b, v214
	v_mul_f32_e32 v187, 0xbfb8aa3b, v215
	v_exp_f32_e32 v183, v183
	v_exp_f32_e32 v187, v187
	v_cvt_pk_bf16_f32 v245, v148, v149
	v_pk_fma_f32 v[148:149], v[8:9], v[200:201], v[144:145] op_sel_hi:[1,0,1]
	v_pk_fma_f32 v[138:139], v[2:3], v[200:201], v[138:139] op_sel_hi:[1,0,1]
	v_pk_fma_f32 v[136:137], v[48:49], v[200:201], v[136:137] op_sel_hi:[1,0,1]
	v_pk_fma_f32 v[130:131], v[38:39], v[200:201], v[130:131] op_sel_hi:[1,0,1]
	v_cvt_pk_bf16_f32 v144, v142, v143
	v_mul_f32_e32 v142, 0xbfb8aa3b, v148
	v_mul_f32_e32 v143, 0xbfb8aa3b, v149
	v_mul_f32_e32 v138, 0xbfb8aa3b, v138
	v_mul_f32_e32 v139, 0xbfb8aa3b, v139
	v_cvt_pk_bf16_f32 v134, v134, v135
	v_mul_f32_e32 v135, 0xbfb8aa3b, v136
	v_mul_f32_e32 v136, 0xbfb8aa3b, v137
	v_mul_f32_e32 v130, 0xbfb8aa3b, v130
	v_mul_f32_e32 v131, 0xbfb8aa3b, v131
	v_exp_f32_e32 v142, v142
	v_exp_f32_e32 v143, v143
	v_exp_f32_e32 v138, v138
	v_exp_f32_e32 v139, v139
	v_exp_f32_e32 v135, v135
	v_exp_f32_e32 v136, v136
	v_exp_f32_e32 v130, v130
	v_exp_f32_e32 v131, v131
	v_add_f32_e32 v183, 1.0, v183
	v_add_f32_e32 v187, 1.0, v187
	v_rcp_f32_e32 v183, v183
	v_rcp_f32_e32 v187, v187
	v_add_f32_e32 v142, 1.0, v142
	v_add_f32_e32 v143, 1.0, v143
	v_add_f32_e32 v138, 1.0, v138
	v_add_f32_e32 v139, 1.0, v139
	v_add_f32_e32 v135, 1.0, v135
	v_add_f32_e32 v136, 1.0, v136
	v_add_f32_e32 v130, 1.0, v130
	v_add_f32_e32 v131, 1.0, v131
	v_rcp_f32_e32 v142, v142
	v_rcp_f32_e32 v143, v143
	v_rcp_f32_e32 v138, v138
	v_rcp_f32_e32 v139, v139
	v_rcp_f32_e32 v135, v135
	v_rcp_f32_e32 v136, v136
	v_rcp_f32_e32 v130, v130
	v_rcp_f32_e32 v131, v131
	v_cvt_pk_bf16_f32 v244, v183, v187
	global_store_dwordx4 v[146:147], v[242:245], off offset:256
	v_lshlrev_b64 v[146:147], 11, v[196:197]
	v_lshl_add_u64 v[146:147], s[2:3], 0, v[146:147]
	v_pk_fma_f32 v[140:141], v[4:5], v[200:201], v[140:141] op_sel_hi:[1,0,1]
	v_pk_fma_f32 v[132:133], v[40:41], v[200:201], v[132:133] op_sel_hi:[1,0,1]
	v_cvt_pk_bf16_f32 v145, v142, v143
	v_lshl_add_u64 v[142:143], v[146:147], 0, v[0:1]
	v_cvt_pk_bf16_f32 v146, v138, v139
	v_mul_f32_e32 v138, 0xbfb8aa3b, v140
	v_mul_f32_e32 v139, 0xbfb8aa3b, v141
	v_cvt_pk_bf16_f32 v135, v135, v136
	v_cvt_pk_bf16_f32 v136, v130, v131
	v_mul_f32_e32 v130, 0xbfb8aa3b, v132
	v_mul_f32_e32 v131, 0xbfb8aa3b, v133
	v_exp_f32_e32 v138, v138
	v_exp_f32_e32 v139, v139
	v_exp_f32_e32 v130, v130
	v_exp_f32_e32 v131, v131
	v_add_f32_e32 v138, 1.0, v138
	v_add_f32_e32 v139, 1.0, v139
	v_add_f32_e32 v130, 1.0, v130
	v_add_f32_e32 v131, 1.0, v131
	v_rcp_f32_e32 v138, v138
	v_rcp_f32_e32 v139, v139
	v_rcp_f32_e32 v130, v130
	v_rcp_f32_e32 v131, v131
	v_cvt_pk_bf16_f32 v147, v138, v139
	global_store_dwordx4 v[142:143], v[144:147], off
	v_cvt_pk_bf16_f32 v137, v130, v131
	global_store_dwordx4 v[142:143], v[134:137], off offset:256
	s_cbranch_execnz .LBB0_181
